# P11 kind-0 residual epilogue: loads batched per row group, 2-deep pipelined (hand-written), bit-identical math
# speedup vs baseline: 1.0038x; 1.0038x over previous
;     static __device__ __forceinline__ const void* rowptr(const void* b, size_t r, int ldc) { if constexpr (BASE_BF16) return (const bf16_t*)b + r * ldc; else return (const float*)b + r * ldc; }
;     static __device__ __forceinline__ void stq(bf16_t* p, f32x4 v) { u32x2 w; w.x = cvt_pk_bf16(v[0], v[1]); w.y = cvt_pk_bf16(v[2], v[3]); *(u32x2*)p = w; }
;     __device__ __forceinline__ void operator()(const f32x4 (&acc)[2][2][4][2], const Unit& u, int wr, int wc, int fr, int fq) const {
;     ...
;             for (int ai = 0; ai < 2; ++ai)
; #pragma unroll
;                 for (int m = 0; m < 4; ++m) { const int r = u.pm * BM + ai * HALF + wr * 64 + m * 16 + fr;
;                     const void* brow = (r < split_rows) ? rowptr(base_p, (size_t)r, ldc) : rowptr(base_s, (size_t)(r - split_rows), ldc);
;                     const float* grow = mod + (size_t)((r < split_rows) ? 0 : 1 + ((r - split_rows) >> 3)) * modld + goff;
;                     bf16_t* orow = out + (size_t)r * ldc;
; #pragma unroll
;                     for (int bj = 0; bj < 2; ++bj)
; #pragma unroll
;                         for (int n = 0; n < 2; ++n) { const int c = col0 + bj * HALF + n * 16;
;                             const f32x4 b = ldb(brow, c), g = *(const f32x4*)(grow + c);
;                             stq(orow + c, b + (g * gs) * acc[ai][bj][m][n]); }
;                     asm volatile("" ::: "memory"); }
.LBB0_1050:
	v_lshl_add_u32 v4, s1, 8, v180
	v_lshl_or_b32 v2, s0, 8, v212
	s_add_u32 s26, s56, 0x20000
	s_addc_u32 s27, s57, 0
	v_lshlrev_b32_e32 v3, 1, v2
	v_lshlrev_b32_e32 v5, 2, v2
	v_lshl_add_u32 v6, v4, 13, v3
	v_add_u32_e32 v28, 0xffffe000, v4
	v_ashrrev_i32_e32 v28, 3, v28
	v_add_u32_e32 v28, 1, v28
	v_max_i32_e32 v28, 0, v28
	v_mad_u32_u24 v14, v28, s79, v5
	v_add_u32_e32 v7, 0x20000, v6
	v_add_u32_e32 v28, 0xffffe010, v4
	v_ashrrev_i32_e32 v28, 3, v28
	v_add_u32_e32 v28, 1, v28
	v_max_i32_e32 v28, 0, v28
	v_mad_u32_u24 v15, v28, s79, v5
	v_add_u32_e32 v8, 0x40000, v6
	v_add_u32_e32 v28, 0xffffe020, v4
	v_ashrrev_i32_e32 v28, 3, v28
	v_add_u32_e32 v28, 1, v28
	v_max_i32_e32 v28, 0, v28
	v_mad_u32_u24 v16, v28, s79, v5
	v_add_u32_e32 v9, 0x60000, v6
	v_add_u32_e32 v28, 0xffffe030, v4
	v_ashrrev_i32_e32 v28, 3, v28
	v_add_u32_e32 v28, 1, v28
	v_max_i32_e32 v28, 0, v28
	v_mad_u32_u24 v17, v28, s79, v5
	v_add_u32_e32 v10, 0x100000, v6
	v_add_u32_e32 v28, 0xffffe080, v4
	v_ashrrev_i32_e32 v28, 3, v28
	v_add_u32_e32 v28, 1, v28
	v_max_i32_e32 v28, 0, v28
	v_mad_u32_u24 v18, v28, s79, v5
	v_add_u32_e32 v11, 0x120000, v6
	v_add_u32_e32 v28, 0xffffe090, v4
	v_ashrrev_i32_e32 v28, 3, v28
	v_add_u32_e32 v28, 1, v28
	v_max_i32_e32 v28, 0, v28
	v_mad_u32_u24 v19, v28, s79, v5
	v_add_u32_e32 v12, 0x140000, v6
	v_add_u32_e32 v28, 0xffffe0a0, v4
	v_ashrrev_i32_e32 v28, 3, v28
	v_add_u32_e32 v28, 1, v28
	v_max_i32_e32 v28, 0, v28
	v_mad_u32_u24 v20, v28, s79, v5
	v_add_u32_e32 v13, 0x160000, v6
	v_add_u32_e32 v28, 0xffffe0b0, v4
	v_ashrrev_i32_e32 v28, 3, v28
	v_add_u32_e32 v28, 1, v28
	v_max_i32_e32 v28, 0, v28
	v_mad_u32_u24 v21, v28, s79, v5
	global_load_dwordx2 v[214:215], v6, s[68:69]
	global_load_dwordx2 v[216:217], v6, s[68:69] offset:32
	global_load_dwordx2 v[218:219], v6, s[68:69] offset:256
	global_load_dwordx2 v[220:221], v6, s[68:69] offset:288
	global_load_dwordx4 v[222:225], v14, s[26:27]
	global_load_dwordx4 v[226:229], v14, s[26:27] offset:64
	global_load_dwordx4 v[230:233], v14, s[26:27] offset:512
	global_load_dwordx4 v[234:237], v14, s[26:27] offset:576
	global_load_dwordx2 v[238:239], v7, s[68:69]
	global_load_dwordx2 v[240:241], v7, s[68:69] offset:32
	global_load_dwordx2 v[242:243], v7, s[68:69] offset:256
	global_load_dwordx2 v[244:245], v7, s[68:69] offset:288
	global_load_dwordx4 v[246:249], v15, s[26:27]
	global_load_dwordx4 v[172:175], v15, s[26:27] offset:64
	global_load_dwordx4 v[176:179], v15, s[26:27] offset:512
	global_load_dwordx4 v[30:33], v15, s[26:27] offset:576
	s_waitcnt vmcnt(8)
	v_lshlrev_b32_e32 v22, 16, v214
	v_and_b32_e32 v23, 0xffff0000, v214
	v_pk_mul_f32 v[222:223], v[222:223], s[44:45] op_sel_hi:[1,0]
	v_lshlrev_b32_e32 v24, 16, v215
	v_and_b32_e32 v25, 0xffff0000, v215
	v_pk_mul_f32 v[224:225], v[224:225], s[44:45] op_sel_hi:[1,0]
	v_pk_fma_f32 v[22:23], v[222:223], v[158:159], v[22:23]
	v_pk_fma_f32 v[24:25], v[224:225], v[160:161], v[24:25]
	v_cvt_pk_bf16_f32 v26, v22, v23
	v_cvt_pk_bf16_f32 v27, v24, v25
	global_store_dwordx2 v6, v[26:27], s[68:69]
	v_lshlrev_b32_e32 v22, 16, v216
	v_and_b32_e32 v23, 0xffff0000, v216
	v_pk_mul_f32 v[226:227], v[226:227], s[44:45] op_sel_hi:[1,0]
	v_lshlrev_b32_e32 v24, 16, v217
	v_and_b32_e32 v25, 0xffff0000, v217
	v_pk_mul_f32 v[228:229], v[228:229], s[44:45] op_sel_hi:[1,0]
	v_pk_fma_f32 v[22:23], v[226:227], v[154:155], v[22:23]
	v_pk_fma_f32 v[24:25], v[228:229], v[156:157], v[24:25]
	v_cvt_pk_bf16_f32 v26, v22, v23
	v_cvt_pk_bf16_f32 v27, v24, v25
	global_store_dwordx2 v6, v[26:27], s[68:69] offset:32
	v_lshlrev_b32_e32 v22, 16, v218
	v_and_b32_e32 v23, 0xffff0000, v218
	v_pk_mul_f32 v[230:231], v[230:231], s[44:45] op_sel_hi:[1,0]
	v_lshlrev_b32_e32 v24, 16, v219
	v_and_b32_e32 v25, 0xffff0000, v219
	v_pk_mul_f32 v[232:233], v[232:233], s[44:45] op_sel_hi:[1,0]
	v_pk_fma_f32 v[22:23], v[230:231], v[126:127], v[22:23]
	v_pk_fma_f32 v[24:25], v[232:233], v[128:129], v[24:25]
	v_cvt_pk_bf16_f32 v26, v22, v23
	v_cvt_pk_bf16_f32 v27, v24, v25
	global_store_dwordx2 v6, v[26:27], s[68:69] offset:256
	v_lshlrev_b32_e32 v22, 16, v220
	v_and_b32_e32 v23, 0xffff0000, v220
	v_pk_mul_f32 v[234:235], v[234:235], s[44:45] op_sel_hi:[1,0]
	v_lshlrev_b32_e32 v24, 16, v221
	v_and_b32_e32 v25, 0xffff0000, v221
	v_pk_mul_f32 v[236:237], v[236:237], s[44:45] op_sel_hi:[1,0]
	v_pk_fma_f32 v[22:23], v[234:235], v[122:123], v[22:23]
	v_pk_fma_f32 v[24:25], v[236:237], v[124:125], v[24:25]
	v_cvt_pk_bf16_f32 v26, v22, v23
	v_cvt_pk_bf16_f32 v27, v24, v25
	global_store_dwordx2 v6, v[26:27], s[68:69] offset:288
	global_load_dwordx2 v[214:215], v8, s[68:69]
	global_load_dwordx2 v[216:217], v8, s[68:69] offset:32
	global_load_dwordx2 v[218:219], v8, s[68:69] offset:256
	global_load_dwordx2 v[220:221], v8, s[68:69] offset:288
	global_load_dwordx4 v[222:225], v16, s[26:27]
	global_load_dwordx4 v[226:229], v16, s[26:27] offset:64
	global_load_dwordx4 v[230:233], v16, s[26:27] offset:512
	global_load_dwordx4 v[234:237], v16, s[26:27] offset:576
	s_waitcnt vmcnt(12)
;     static __device__ __forceinline__ const void* rowptr(const void* b, size_t r, int ldc) { if constexpr (BASE_BF16) return (const bf16_t*)b + r * ldc; else return (const float*)b + r * ldc; }
;     static __device__ __forceinline__ void stq(bf16_t* p, f32x4 v) { u32x2 w; w.x = cvt_pk_bf16(v[0], v[1]); w.y = cvt_pk_bf16(v[2], v[3]); *(u32x2*)p = w; }
;     __device__ __forceinline__ void operator()(const f32x4 (&acc)[2][2][4][2], const Unit& u, int wr, int wc, int fr, int fq) const {
;     ...
;             for (int ai = 0; ai < 2; ++ai)
; #pragma unroll
;                 for (int m = 0; m < 4; ++m) { const int r = u.pm * BM + ai * HALF + wr * 64 + m * 16 + fr;
;                     const void* brow = (r < split_rows) ? rowptr(base_p, (size_t)r, ldc) : rowptr(base_s, (size_t)(r - split_rows), ldc);
;                     const float* grow = mod + (size_t)((r < split_rows) ? 0 : 1 + ((r - split_rows) >> 3)) * modld + goff;
;                     bf16_t* orow = out + (size_t)r * ldc;
; #pragma unroll
;                     for (int bj = 0; bj < 2; ++bj)
; #pragma unroll
;                         for (int n = 0; n < 2; ++n) { const int c = col0 + bj * HALF + n * 16;
;                             const f32x4 b = ldb(brow, c), g = *(const f32x4*)(grow + c);
;                             stq(orow + c, b + (g * gs) * acc[ai][bj][m][n]); }
;                     asm volatile("" ::: "memory"); }
	v_lshlrev_b32_e32 v22, 16, v238
	v_and_b32_e32 v23, 0xffff0000, v238
	v_pk_mul_f32 v[246:247], v[246:247], s[44:45] op_sel_hi:[1,0]
	v_lshlrev_b32_e32 v24, 16, v239
	v_and_b32_e32 v25, 0xffff0000, v239
	v_pk_mul_f32 v[248:249], v[248:249], s[44:45] op_sel_hi:[1,0]
	v_pk_fma_f32 v[22:23], v[246:247], v[150:151], v[22:23]
	v_pk_fma_f32 v[24:25], v[248:249], v[152:153], v[24:25]
	v_cvt_pk_bf16_f32 v26, v22, v23
	v_cvt_pk_bf16_f32 v27, v24, v25
	global_store_dwordx2 v7, v[26:27], s[68:69]
	v_lshlrev_b32_e32 v22, 16, v240
	v_and_b32_e32 v23, 0xffff0000, v240
	v_pk_mul_f32 v[172:173], v[172:173], s[44:45] op_sel_hi:[1,0]
	v_lshlrev_b32_e32 v24, 16, v241
	v_and_b32_e32 v25, 0xffff0000, v241
	v_pk_mul_f32 v[174:175], v[174:175], s[44:45] op_sel_hi:[1,0]
	v_pk_fma_f32 v[22:23], v[172:173], v[146:147], v[22:23]
	v_pk_fma_f32 v[24:25], v[174:175], v[148:149], v[24:25]
	v_cvt_pk_bf16_f32 v26, v22, v23
	v_cvt_pk_bf16_f32 v27, v24, v25
	global_store_dwordx2 v7, v[26:27], s[68:69] offset:32
	v_lshlrev_b32_e32 v22, 16, v242
	v_and_b32_e32 v23, 0xffff0000, v242
	v_pk_mul_f32 v[176:177], v[176:177], s[44:45] op_sel_hi:[1,0]
	v_lshlrev_b32_e32 v24, 16, v243
	v_and_b32_e32 v25, 0xffff0000, v243
	v_pk_mul_f32 v[178:179], v[178:179], s[44:45] op_sel_hi:[1,0]
	v_pk_fma_f32 v[22:23], v[176:177], v[118:119], v[22:23]
	v_pk_fma_f32 v[24:25], v[178:179], v[120:121], v[24:25]
	v_cvt_pk_bf16_f32 v26, v22, v23
	v_cvt_pk_bf16_f32 v27, v24, v25
	global_store_dwordx2 v7, v[26:27], s[68:69] offset:256
	v_lshlrev_b32_e32 v22, 16, v244
	v_and_b32_e32 v23, 0xffff0000, v244
	v_pk_mul_f32 v[30:31], v[30:31], s[44:45] op_sel_hi:[1,0]
	v_lshlrev_b32_e32 v24, 16, v245
	v_and_b32_e32 v25, 0xffff0000, v245
	v_pk_mul_f32 v[32:33], v[32:33], s[44:45] op_sel_hi:[1,0]
	v_pk_fma_f32 v[22:23], v[30:31], v[114:115], v[22:23]
	v_pk_fma_f32 v[24:25], v[32:33], v[116:117], v[24:25]
	v_cvt_pk_bf16_f32 v26, v22, v23
	v_cvt_pk_bf16_f32 v27, v24, v25
	global_store_dwordx2 v7, v[26:27], s[68:69] offset:288
	global_load_dwordx2 v[238:239], v9, s[68:69]
	global_load_dwordx2 v[240:241], v9, s[68:69] offset:32
	global_load_dwordx2 v[242:243], v9, s[68:69] offset:256
	global_load_dwordx2 v[244:245], v9, s[68:69] offset:288
	global_load_dwordx4 v[246:249], v17, s[26:27]
	global_load_dwordx4 v[172:175], v17, s[26:27] offset:64
	global_load_dwordx4 v[176:179], v17, s[26:27] offset:512
	global_load_dwordx4 v[30:33], v17, s[26:27] offset:576
	s_waitcnt vmcnt(12)
	v_lshlrev_b32_e32 v22, 16, v214
	v_and_b32_e32 v23, 0xffff0000, v214
	v_pk_mul_f32 v[222:223], v[222:223], s[44:45] op_sel_hi:[1,0]
	v_lshlrev_b32_e32 v24, 16, v215
	v_and_b32_e32 v25, 0xffff0000, v215
	v_pk_mul_f32 v[224:225], v[224:225], s[44:45] op_sel_hi:[1,0]
	v_pk_fma_f32 v[22:23], v[222:223], v[142:143], v[22:23]
	v_pk_fma_f32 v[24:25], v[224:225], v[144:145], v[24:25]
	v_cvt_pk_bf16_f32 v26, v22, v23
	v_cvt_pk_bf16_f32 v27, v24, v25
	global_store_dwordx2 v8, v[26:27], s[68:69]
	v_lshlrev_b32_e32 v22, 16, v216
	v_and_b32_e32 v23, 0xffff0000, v216
	v_pk_mul_f32 v[226:227], v[226:227], s[44:45] op_sel_hi:[1,0]
	v_lshlrev_b32_e32 v24, 16, v217
	v_and_b32_e32 v25, 0xffff0000, v217
	v_pk_mul_f32 v[228:229], v[228:229], s[44:45] op_sel_hi:[1,0]
	v_pk_fma_f32 v[22:23], v[226:227], v[138:139], v[22:23]
	v_pk_fma_f32 v[24:25], v[228:229], v[140:141], v[24:25]
	v_cvt_pk_bf16_f32 v26, v22, v23
	v_cvt_pk_bf16_f32 v27, v24, v25
	global_store_dwordx2 v8, v[26:27], s[68:69] offset:32
	v_lshlrev_b32_e32 v22, 16, v218
	v_and_b32_e32 v23, 0xffff0000, v218
	v_pk_mul_f32 v[230:231], v[230:231], s[44:45] op_sel_hi:[1,0]
	v_lshlrev_b32_e32 v24, 16, v219
	v_and_b32_e32 v25, 0xffff0000, v219
	v_pk_mul_f32 v[232:233], v[232:233], s[44:45] op_sel_hi:[1,0]
	v_pk_fma_f32 v[22:23], v[230:231], v[110:111], v[22:23]
	v_pk_fma_f32 v[24:25], v[232:233], v[112:113], v[24:25]
	v_cvt_pk_bf16_f32 v26, v22, v23
	v_cvt_pk_bf16_f32 v27, v24, v25
	global_store_dwordx2 v8, v[26:27], s[68:69] offset:256
	v_lshlrev_b32_e32 v22, 16, v220
	v_and_b32_e32 v23, 0xffff0000, v220
	v_pk_mul_f32 v[234:235], v[234:235], s[44:45] op_sel_hi:[1,0]
	v_lshlrev_b32_e32 v24, 16, v221
	v_and_b32_e32 v25, 0xffff0000, v221
	v_pk_mul_f32 v[236:237], v[236:237], s[44:45] op_sel_hi:[1,0]
	v_pk_fma_f32 v[22:23], v[234:235], v[106:107], v[22:23]
	v_pk_fma_f32 v[24:25], v[236:237], v[108:109], v[24:25]
	v_cvt_pk_bf16_f32 v26, v22, v23
	v_cvt_pk_bf16_f32 v27, v24, v25
	global_store_dwordx2 v8, v[26:27], s[68:69] offset:288
	global_load_dwordx2 v[214:215], v10, s[68:69]
	global_load_dwordx2 v[216:217], v10, s[68:69] offset:32
	global_load_dwordx2 v[218:219], v10, s[68:69] offset:256
	global_load_dwordx2 v[220:221], v10, s[68:69] offset:288
	global_load_dwordx4 v[222:225], v18, s[26:27]
	global_load_dwordx4 v[226:229], v18, s[26:27] offset:64
	global_load_dwordx4 v[230:233], v18, s[26:27] offset:512
	global_load_dwordx4 v[234:237], v18, s[26:27] offset:576
	s_waitcnt vmcnt(12)
;     static __device__ __forceinline__ const void* rowptr(const void* b, size_t r, int ldc) { if constexpr (BASE_BF16) return (const bf16_t*)b + r * ldc; else return (const float*)b + r * ldc; }
;     static __device__ __forceinline__ void stq(bf16_t* p, f32x4 v) { u32x2 w; w.x = cvt_pk_bf16(v[0], v[1]); w.y = cvt_pk_bf16(v[2], v[3]); *(u32x2*)p = w; }
;     __device__ __forceinline__ void operator()(const f32x4 (&acc)[2][2][4][2], const Unit& u, int wr, int wc, int fr, int fq) const {
;     ...
;             for (int ai = 0; ai < 2; ++ai)
; #pragma unroll
;                 for (int m = 0; m < 4; ++m) { const int r = u.pm * BM + ai * HALF + wr * 64 + m * 16 + fr;
;                     const void* brow = (r < split_rows) ? rowptr(base_p, (size_t)r, ldc) : rowptr(base_s, (size_t)(r - split_rows), ldc);
;                     const float* grow = mod + (size_t)((r < split_rows) ? 0 : 1 + ((r - split_rows) >> 3)) * modld + goff;
;                     bf16_t* orow = out + (size_t)r * ldc;
; #pragma unroll
;                     for (int bj = 0; bj < 2; ++bj)
; #pragma unroll
;                         for (int n = 0; n < 2; ++n) { const int c = col0 + bj * HALF + n * 16;
;                             const f32x4 b = ldb(brow, c), g = *(const f32x4*)(grow + c);
;                             stq(orow + c, b + (g * gs) * acc[ai][bj][m][n]); }
;                     asm volatile("" ::: "memory"); }
	v_lshlrev_b32_e32 v22, 16, v238
	v_and_b32_e32 v23, 0xffff0000, v238
	v_pk_mul_f32 v[246:247], v[246:247], s[44:45] op_sel_hi:[1,0]
	v_lshlrev_b32_e32 v24, 16, v239
	v_and_b32_e32 v25, 0xffff0000, v239
	v_pk_mul_f32 v[248:249], v[248:249], s[44:45] op_sel_hi:[1,0]
	v_pk_fma_f32 v[22:23], v[246:247], v[134:135], v[22:23]
	v_pk_fma_f32 v[24:25], v[248:249], v[136:137], v[24:25]
	v_cvt_pk_bf16_f32 v26, v22, v23
	v_cvt_pk_bf16_f32 v27, v24, v25
	global_store_dwordx2 v9, v[26:27], s[68:69]
	v_lshlrev_b32_e32 v22, 16, v240
	v_and_b32_e32 v23, 0xffff0000, v240
	v_pk_mul_f32 v[172:173], v[172:173], s[44:45] op_sel_hi:[1,0]
	v_lshlrev_b32_e32 v24, 16, v241
	v_and_b32_e32 v25, 0xffff0000, v241
	v_pk_mul_f32 v[174:175], v[174:175], s[44:45] op_sel_hi:[1,0]
	v_pk_fma_f32 v[22:23], v[172:173], v[130:131], v[22:23]
	v_pk_fma_f32 v[24:25], v[174:175], v[132:133], v[24:25]
	v_cvt_pk_bf16_f32 v26, v22, v23
	v_cvt_pk_bf16_f32 v27, v24, v25
	global_store_dwordx2 v9, v[26:27], s[68:69] offset:32
	v_lshlrev_b32_e32 v22, 16, v242
	v_and_b32_e32 v23, 0xffff0000, v242
	v_pk_mul_f32 v[176:177], v[176:177], s[44:45] op_sel_hi:[1,0]
	v_lshlrev_b32_e32 v24, 16, v243
	v_and_b32_e32 v25, 0xffff0000, v243
	v_pk_mul_f32 v[178:179], v[178:179], s[44:45] op_sel_hi:[1,0]
	v_pk_fma_f32 v[22:23], v[176:177], v[102:103], v[22:23]
	v_pk_fma_f32 v[24:25], v[178:179], v[104:105], v[24:25]
	v_cvt_pk_bf16_f32 v26, v22, v23
	v_cvt_pk_bf16_f32 v27, v24, v25
	global_store_dwordx2 v9, v[26:27], s[68:69] offset:256
	v_lshlrev_b32_e32 v22, 16, v244
	v_and_b32_e32 v23, 0xffff0000, v244
	v_pk_mul_f32 v[30:31], v[30:31], s[44:45] op_sel_hi:[1,0]
	v_lshlrev_b32_e32 v24, 16, v245
	v_and_b32_e32 v25, 0xffff0000, v245
	v_pk_mul_f32 v[32:33], v[32:33], s[44:45] op_sel_hi:[1,0]
	v_pk_fma_f32 v[22:23], v[30:31], v[98:99], v[22:23]
	v_pk_fma_f32 v[24:25], v[32:33], v[100:101], v[24:25]
	v_cvt_pk_bf16_f32 v26, v22, v23
	v_cvt_pk_bf16_f32 v27, v24, v25
	global_store_dwordx2 v9, v[26:27], s[68:69] offset:288
	global_load_dwordx2 v[238:239], v11, s[68:69]
	global_load_dwordx2 v[240:241], v11, s[68:69] offset:32
	global_load_dwordx2 v[242:243], v11, s[68:69] offset:256
	global_load_dwordx2 v[244:245], v11, s[68:69] offset:288
	global_load_dwordx4 v[246:249], v19, s[26:27]
	global_load_dwordx4 v[172:175], v19, s[26:27] offset:64
	global_load_dwordx4 v[176:179], v19, s[26:27] offset:512
	global_load_dwordx4 v[30:33], v19, s[26:27] offset:576
	s_waitcnt vmcnt(12)
	v_lshlrev_b32_e32 v22, 16, v214
	v_and_b32_e32 v23, 0xffff0000, v214
	v_pk_mul_f32 v[222:223], v[222:223], s[44:45] op_sel_hi:[1,0]
	v_lshlrev_b32_e32 v24, 16, v215
	v_and_b32_e32 v25, 0xffff0000, v215
	v_pk_mul_f32 v[224:225], v[224:225], s[44:45] op_sel_hi:[1,0]
	v_pk_fma_f32 v[22:23], v[222:223], v[94:95], v[22:23]
	v_pk_fma_f32 v[24:25], v[224:225], v[96:97], v[24:25]
	v_cvt_pk_bf16_f32 v26, v22, v23
	v_cvt_pk_bf16_f32 v27, v24, v25
	global_store_dwordx2 v10, v[26:27], s[68:69]
	v_lshlrev_b32_e32 v22, 16, v216
	v_and_b32_e32 v23, 0xffff0000, v216
	v_pk_mul_f32 v[226:227], v[226:227], s[44:45] op_sel_hi:[1,0]
	v_lshlrev_b32_e32 v24, 16, v217
	v_and_b32_e32 v25, 0xffff0000, v217
	v_pk_mul_f32 v[228:229], v[228:229], s[44:45] op_sel_hi:[1,0]
	v_pk_fma_f32 v[22:23], v[226:227], v[90:91], v[22:23]
	v_pk_fma_f32 v[24:25], v[228:229], v[92:93], v[24:25]
	v_cvt_pk_bf16_f32 v26, v22, v23
	v_cvt_pk_bf16_f32 v27, v24, v25
	global_store_dwordx2 v10, v[26:27], s[68:69] offset:32
	v_lshlrev_b32_e32 v22, 16, v218
	v_and_b32_e32 v23, 0xffff0000, v218
	v_pk_mul_f32 v[230:231], v[230:231], s[44:45] op_sel_hi:[1,0]
	v_lshlrev_b32_e32 v24, 16, v219
	v_and_b32_e32 v25, 0xffff0000, v219
	v_pk_mul_f32 v[232:233], v[232:233], s[44:45] op_sel_hi:[1,0]
	v_pk_fma_f32 v[22:23], v[230:231], v[62:63], v[22:23]
	v_pk_fma_f32 v[24:25], v[232:233], v[64:65], v[24:25]
	v_cvt_pk_bf16_f32 v26, v22, v23
	v_cvt_pk_bf16_f32 v27, v24, v25
	global_store_dwordx2 v10, v[26:27], s[68:69] offset:256
	v_lshlrev_b32_e32 v22, 16, v220
	v_and_b32_e32 v23, 0xffff0000, v220
	v_pk_mul_f32 v[234:235], v[234:235], s[44:45] op_sel_hi:[1,0]
	v_lshlrev_b32_e32 v24, 16, v221
	v_and_b32_e32 v25, 0xffff0000, v221
	v_pk_mul_f32 v[236:237], v[236:237], s[44:45] op_sel_hi:[1,0]
	v_pk_fma_f32 v[22:23], v[234:235], v[58:59], v[22:23]
	v_pk_fma_f32 v[24:25], v[236:237], v[60:61], v[24:25]
	v_cvt_pk_bf16_f32 v26, v22, v23
	v_cvt_pk_bf16_f32 v27, v24, v25
	global_store_dwordx2 v10, v[26:27], s[68:69] offset:288
	global_load_dwordx2 v[214:215], v12, s[68:69]
	global_load_dwordx2 v[216:217], v12, s[68:69] offset:32
	global_load_dwordx2 v[218:219], v12, s[68:69] offset:256
	global_load_dwordx2 v[220:221], v12, s[68:69] offset:288
	global_load_dwordx4 v[222:225], v20, s[26:27]
	global_load_dwordx4 v[226:229], v20, s[26:27] offset:64
	global_load_dwordx4 v[230:233], v20, s[26:27] offset:512
	global_load_dwordx4 v[234:237], v20, s[26:27] offset:576
	s_waitcnt vmcnt(12)
;     static __device__ __forceinline__ const void* rowptr(const void* b, size_t r, int ldc) { if constexpr (BASE_BF16) return (const bf16_t*)b + r * ldc; else return (const float*)b + r * ldc; }
;     static __device__ __forceinline__ void stq(bf16_t* p, f32x4 v) { u32x2 w; w.x = cvt_pk_bf16(v[0], v[1]); w.y = cvt_pk_bf16(v[2], v[3]); *(u32x2*)p = w; }
;     __device__ __forceinline__ void operator()(const f32x4 (&acc)[2][2][4][2], const Unit& u, int wr, int wc, int fr, int fq) const {
;     ...
;             for (int ai = 0; ai < 2; ++ai)
; #pragma unroll
;                 for (int m = 0; m < 4; ++m) { const int r = u.pm * BM + ai * HALF + wr * 64 + m * 16 + fr;
;                     const void* brow = (r < split_rows) ? rowptr(base_p, (size_t)r, ldc) : rowptr(base_s, (size_t)(r - split_rows), ldc);
;                     const float* grow = mod + (size_t)((r < split_rows) ? 0 : 1 + ((r - split_rows) >> 3)) * modld + goff;
;                     bf16_t* orow = out + (size_t)r * ldc;
; #pragma unroll
;                     for (int bj = 0; bj < 2; ++bj)
; #pragma unroll
;                         for (int n = 0; n < 2; ++n) { const int c = col0 + bj * HALF + n * 16;
;                             const f32x4 b = ldb(brow, c), g = *(const f32x4*)(grow + c);
;                             stq(orow + c, b + (g * gs) * acc[ai][bj][m][n]); }
;                     asm volatile("" ::: "memory"); }
	v_lshlrev_b32_e32 v22, 16, v238
	v_and_b32_e32 v23, 0xffff0000, v238
	v_pk_mul_f32 v[246:247], v[246:247], s[44:45] op_sel_hi:[1,0]
	v_lshlrev_b32_e32 v24, 16, v239
	v_and_b32_e32 v25, 0xffff0000, v239
	v_pk_mul_f32 v[248:249], v[248:249], s[44:45] op_sel_hi:[1,0]
	v_pk_fma_f32 v[22:23], v[246:247], v[86:87], v[22:23]
	v_pk_fma_f32 v[24:25], v[248:249], v[88:89], v[24:25]
	v_cvt_pk_bf16_f32 v26, v22, v23
	v_cvt_pk_bf16_f32 v27, v24, v25
	global_store_dwordx2 v11, v[26:27], s[68:69]
	v_lshlrev_b32_e32 v22, 16, v240
	v_and_b32_e32 v23, 0xffff0000, v240
	v_pk_mul_f32 v[172:173], v[172:173], s[44:45] op_sel_hi:[1,0]
	v_lshlrev_b32_e32 v24, 16, v241
	v_and_b32_e32 v25, 0xffff0000, v241
	v_pk_mul_f32 v[174:175], v[174:175], s[44:45] op_sel_hi:[1,0]
	v_pk_fma_f32 v[22:23], v[172:173], v[82:83], v[22:23]
	v_pk_fma_f32 v[24:25], v[174:175], v[84:85], v[24:25]
	v_cvt_pk_bf16_f32 v26, v22, v23
	v_cvt_pk_bf16_f32 v27, v24, v25
	global_store_dwordx2 v11, v[26:27], s[68:69] offset:32
	v_lshlrev_b32_e32 v22, 16, v242
	v_and_b32_e32 v23, 0xffff0000, v242
	v_pk_mul_f32 v[176:177], v[176:177], s[44:45] op_sel_hi:[1,0]
	v_lshlrev_b32_e32 v24, 16, v243
	v_and_b32_e32 v25, 0xffff0000, v243
	v_pk_mul_f32 v[178:179], v[178:179], s[44:45] op_sel_hi:[1,0]
	v_pk_fma_f32 v[22:23], v[176:177], v[54:55], v[22:23]
	v_pk_fma_f32 v[24:25], v[178:179], v[56:57], v[24:25]
	v_cvt_pk_bf16_f32 v26, v22, v23
	v_cvt_pk_bf16_f32 v27, v24, v25
	global_store_dwordx2 v11, v[26:27], s[68:69] offset:256
	v_lshlrev_b32_e32 v22, 16, v244
	v_and_b32_e32 v23, 0xffff0000, v244
	v_pk_mul_f32 v[30:31], v[30:31], s[44:45] op_sel_hi:[1,0]
	v_lshlrev_b32_e32 v24, 16, v245
	v_and_b32_e32 v25, 0xffff0000, v245
	v_pk_mul_f32 v[32:33], v[32:33], s[44:45] op_sel_hi:[1,0]
	v_pk_fma_f32 v[22:23], v[30:31], v[50:51], v[22:23]
	v_pk_fma_f32 v[24:25], v[32:33], v[52:53], v[24:25]
	v_cvt_pk_bf16_f32 v26, v22, v23
	v_cvt_pk_bf16_f32 v27, v24, v25
	global_store_dwordx2 v11, v[26:27], s[68:69] offset:288
	global_load_dwordx2 v[238:239], v13, s[68:69]
	global_load_dwordx2 v[240:241], v13, s[68:69] offset:32
	global_load_dwordx2 v[242:243], v13, s[68:69] offset:256
	global_load_dwordx2 v[244:245], v13, s[68:69] offset:288
	global_load_dwordx4 v[246:249], v21, s[26:27]
	global_load_dwordx4 v[172:175], v21, s[26:27] offset:64
	global_load_dwordx4 v[176:179], v21, s[26:27] offset:512
	global_load_dwordx4 v[30:33], v21, s[26:27] offset:576
	s_waitcnt vmcnt(12)
	v_lshlrev_b32_e32 v22, 16, v214
	v_and_b32_e32 v23, 0xffff0000, v214
	v_pk_mul_f32 v[222:223], v[222:223], s[44:45] op_sel_hi:[1,0]
	v_lshlrev_b32_e32 v24, 16, v215
	v_and_b32_e32 v25, 0xffff0000, v215
	v_pk_mul_f32 v[224:225], v[224:225], s[44:45] op_sel_hi:[1,0]
	v_pk_fma_f32 v[22:23], v[222:223], v[78:79], v[22:23]
	v_pk_fma_f32 v[24:25], v[224:225], v[80:81], v[24:25]
	v_cvt_pk_bf16_f32 v26, v22, v23
	v_cvt_pk_bf16_f32 v27, v24, v25
	global_store_dwordx2 v12, v[26:27], s[68:69]
	v_lshlrev_b32_e32 v22, 16, v216
	v_and_b32_e32 v23, 0xffff0000, v216
	v_pk_mul_f32 v[226:227], v[226:227], s[44:45] op_sel_hi:[1,0]
	v_lshlrev_b32_e32 v24, 16, v217
	v_and_b32_e32 v25, 0xffff0000, v217
	v_pk_mul_f32 v[228:229], v[228:229], s[44:45] op_sel_hi:[1,0]
	v_pk_fma_f32 v[22:23], v[226:227], v[74:75], v[22:23]
	v_pk_fma_f32 v[24:25], v[228:229], v[76:77], v[24:25]
	v_cvt_pk_bf16_f32 v26, v22, v23
	v_cvt_pk_bf16_f32 v27, v24, v25
	global_store_dwordx2 v12, v[26:27], s[68:69] offset:32
	v_lshlrev_b32_e32 v22, 16, v218
	v_and_b32_e32 v23, 0xffff0000, v218
	v_pk_mul_f32 v[230:231], v[230:231], s[44:45] op_sel_hi:[1,0]
	v_lshlrev_b32_e32 v24, 16, v219
	v_and_b32_e32 v25, 0xffff0000, v219
	v_pk_mul_f32 v[232:233], v[232:233], s[44:45] op_sel_hi:[1,0]
	v_pk_fma_f32 v[22:23], v[230:231], v[46:47], v[22:23]
	v_pk_fma_f32 v[24:25], v[232:233], v[48:49], v[24:25]
	v_cvt_pk_bf16_f32 v26, v22, v23
	v_cvt_pk_bf16_f32 v27, v24, v25
	global_store_dwordx2 v12, v[26:27], s[68:69] offset:256
	v_lshlrev_b32_e32 v22, 16, v220
	v_and_b32_e32 v23, 0xffff0000, v220
	v_pk_mul_f32 v[234:235], v[234:235], s[44:45] op_sel_hi:[1,0]
	v_lshlrev_b32_e32 v24, 16, v221
	v_and_b32_e32 v25, 0xffff0000, v221
	v_pk_mul_f32 v[236:237], v[236:237], s[44:45] op_sel_hi:[1,0]
	v_pk_fma_f32 v[22:23], v[234:235], v[42:43], v[22:23]
	v_pk_fma_f32 v[24:25], v[236:237], v[44:45], v[24:25]
	v_cvt_pk_bf16_f32 v26, v22, v23
	v_cvt_pk_bf16_f32 v27, v24, v25
	global_store_dwordx2 v12, v[26:27], s[68:69] offset:288
	s_waitcnt vmcnt(4)
	v_lshlrev_b32_e32 v22, 16, v238
	v_and_b32_e32 v23, 0xffff0000, v238
	v_pk_mul_f32 v[246:247], v[246:247], s[44:45] op_sel_hi:[1,0]
	v_lshlrev_b32_e32 v24, 16, v239
	v_and_b32_e32 v25, 0xffff0000, v239
	v_pk_mul_f32 v[248:249], v[248:249], s[44:45] op_sel_hi:[1,0]
	v_pk_fma_f32 v[22:23], v[246:247], v[70:71], v[22:23]
	v_pk_fma_f32 v[24:25], v[248:249], v[72:73], v[24:25]
	v_cvt_pk_bf16_f32 v26, v22, v23
	v_cvt_pk_bf16_f32 v27, v24, v25
	global_store_dwordx2 v13, v[26:27], s[68:69]
	v_lshlrev_b32_e32 v22, 16, v240
	v_and_b32_e32 v23, 0xffff0000, v240
	v_pk_mul_f32 v[172:173], v[172:173], s[44:45] op_sel_hi:[1,0]
	v_lshlrev_b32_e32 v24, 16, v241
	v_and_b32_e32 v25, 0xffff0000, v241
	v_pk_mul_f32 v[174:175], v[174:175], s[44:45] op_sel_hi:[1,0]
	v_pk_fma_f32 v[22:23], v[172:173], v[66:67], v[22:23]
	v_pk_fma_f32 v[24:25], v[174:175], v[68:69], v[24:25]
	v_cvt_pk_bf16_f32 v26, v22, v23
	v_cvt_pk_bf16_f32 v27, v24, v25
	global_store_dwordx2 v13, v[26:27], s[68:69] offset:32
	v_lshlrev_b32_e32 v22, 16, v242
	v_and_b32_e32 v23, 0xffff0000, v242
	v_pk_mul_f32 v[176:177], v[176:177], s[44:45] op_sel_hi:[1,0]
	v_lshlrev_b32_e32 v24, 16, v243
	v_and_b32_e32 v25, 0xffff0000, v243
	v_pk_mul_f32 v[178:179], v[178:179], s[44:45] op_sel_hi:[1,0]
	v_pk_fma_f32 v[22:23], v[176:177], v[38:39], v[22:23]
	v_pk_fma_f32 v[24:25], v[178:179], v[40:41], v[24:25]
	v_cvt_pk_bf16_f32 v26, v22, v23
	v_cvt_pk_bf16_f32 v27, v24, v25
	global_store_dwordx2 v13, v[26:27], s[68:69] offset:256
	v_lshlrev_b32_e32 v22, 16, v244
	v_and_b32_e32 v23, 0xffff0000, v244
	v_pk_mul_f32 v[30:31], v[30:31], s[44:45] op_sel_hi:[1,0]
	v_lshlrev_b32_e32 v24, 16, v245
	v_and_b32_e32 v25, 0xffff0000, v245
	v_pk_mul_f32 v[32:33], v[32:33], s[44:45] op_sel_hi:[1,0]
	v_pk_fma_f32 v[22:23], v[30:31], v[34:35], v[22:23]
	v_pk_fma_f32 v[24:25], v[32:33], v[36:37], v[24:25]
	v_cvt_pk_bf16_f32 v26, v22, v23
	v_cvt_pk_bf16_f32 v27, v24, v25
	global_store_dwordx2 v13, v[26:27], s[68:69] offset:288
	s_and_b64 vcc, exec, s[4:5]
	s_cbranch_vccnz .LBB0_1025
	s_branch .LBB0_1048
